# v170 + rotary-table prefetch in the input-projection epilogue + flat grid-barrier release + W_out mid-K rescale factors computed before the K-loop + hot loops page-contained
# speedup vs baseline: 1.0116x; 1.0048x over previous
; #define ATT_SUMPACK(j) do { const float e0_ = (j) < 8 ? P0[2 * ((j) & 7)] : P1[2 * ((j) & 7)], e1_ = (j) < 8 ? P0[2 * ((j) & 7) + 1] : P1[2 * ((j) & 7) + 1]; \
;         if ((j) & 1) { rc += e0_; rd += e1_; } else { ra += e0_; rb += e1_; } S.pw[j] = cvtpk(e0_, e1_); } while (0)
; template <int GRP, bool has_next> __device__ __forceinline__ void att_step(const AttCtx<GRP>& C, AttState<GRP>& S, int s, f32x16& P0, f32x16& P1, f32x16& PN0, f32x16& PN1, u32x4& kreg, u32x4& preg, u32x4& vreg) {
;     ...
;     constexpr int NE = NKS - 1;
;     float ra = 0.f, rb = 0.f, rc = 0.f, rd = 0.f;
;     ...
; #pragma unroll
;     for (int c = 1; c < NKS; ++c) {
;         if (has_next) {
;             if (c == NK0) att_kfrag<GRP, NK0, NK1>(C, (s + 1) & 1, kfb);
;             const bf16x8 a0 = c < NK0 ? kfa[2 * c] : kfb[2 * (c - NK0)], a1 = c < NK0 ? kfa[2 * c + 1] : kfb[2 * (c - NK0) + 1];
;             PN0 = __builtin_amdgcn_mfma_f32_32x32x16_bf16(a0, S.qr[c], PN0, 0, 0, 0); PN1 = __builtin_amdgcn_mfma_f32_32x32x16_bf16(a1, S.qr[c], PN1, 0, 0, 0);
;         }
; #pragma unroll
;         for (int j = (c - 1) * 16 / NE; j < c * 16 / NE; ++j) {
;             if (j < 8) { P0[2 * j] = __builtin_amdgcn_exp2f(P0[2 * j]); P0[2 * j + 1] = __builtin_amdgcn_exp2f(P0[2 * j + 1]); }
;             else { P1[2 * (j - 8)] = __builtin_amdgcn_exp2f(P1[2 * (j - 8)]); P1[2 * (j - 8) + 1] = __builtin_amdgcn_exp2f(P1[2 * (j - 8) + 1]); }
;         }
;         if (c > 1) {
; #pragma unroll
;             for (int j = (c - 2) * 16 / NE; j < (c - 1) * 16 / NE; ++j) ATT_SUMPACK(j);
;         }
;         __builtin_amdgcn_sched_barrier(0);
;     }
;     if (has_next && S.refnz && t != 63) { PN0 = __builtin_amdgcn_mfma_f32_32x32x16_bf16(ones, qx, PN0, 0, 0, 0); PN1 = __builtin_amdgcn_mfma_f32_32x32x16_bf16(ones, qx, PN1, 0, 0, 0); }
;     att_vfrag<GRP>(C, s & 1, vf);
; #pragma unroll
;     for (int j = (NE - 1) * 16 / NE; j < 16; ++j) ATT_SUMPACK(j);
;     ...
;     S.lrun += (ra + rb) + (rc + rd);
.Lmla_nomax1:
	v_exp_f32_e32 v48, v48
	v_exp_f32_e32 v49, v49
	v_exp_f32_e32 v50, v50
	v_exp_f32_e32 v51, v51
	v_cvt_pk_bf16_f32 v216, v48, v49
	v_exp_f32_e32 v52, v52
	v_exp_f32_e32 v53, v53
	v_cvt_pk_bf16_f32 v217, v50, v51
	v_exp_f32_e32 v54, v54
	v_exp_f32_e32 v55, v55
	v_add_f32_e32 v248, v48, v52
	v_add_f32_e32 v249, v49, v53
	v_cvt_pk_bf16_f32 v218, v52, v53
	v_exp_f32_e32 v56, v56
	v_exp_f32_e32 v57, v57
	v_add_f32_e32 v250, v50, v54
	v_add_f32_e32 v251, v51, v55
	v_cvt_pk_bf16_f32 v219, v54, v55
	v_exp_f32_e32 v58, v58
	v_exp_f32_e32 v59, v59
	v_add_f32_e32 v248, v248, v56
	v_add_f32_e32 v249, v249, v57
	v_cvt_pk_bf16_f32 v220, v56, v57
	v_exp_f32_e32 v60, v60
	v_exp_f32_e32 v61, v61
	v_add_f32_e32 v250, v250, v58
	v_add_f32_e32 v251, v251, v59
	v_cvt_pk_bf16_f32 v221, v58, v59
	v_exp_f32_e32 v62, v62
	v_exp_f32_e32 v63, v63
	v_add_f32_e32 v248, v248, v60
	v_add_f32_e32 v249, v249, v61
	v_cvt_pk_bf16_f32 v222, v60, v61
	v_exp_f32_e32 v32, v32
	v_exp_f32_e32 v33, v33
	v_add_f32_e32 v250, v250, v62
	v_add_f32_e32 v251, v251, v63
	v_cvt_pk_bf16_f32 v223, v62, v63
	v_exp_f32_e32 v34, v34
	v_exp_f32_e32 v35, v35
	v_add_f32_e32 v248, v248, v32
	v_add_f32_e32 v249, v249, v33
	v_cvt_pk_bf16_f32 v224, v32, v33
	v_exp_f32_e32 v36, v36
	v_exp_f32_e32 v37, v37
	v_add_f32_e32 v250, v250, v34
	v_add_f32_e32 v251, v251, v35
	v_cvt_pk_bf16_f32 v225, v34, v35
	v_exp_f32_e32 v38, v38
	v_exp_f32_e32 v39, v39
	v_add_f32_e32 v248, v248, v36
	v_add_f32_e32 v249, v249, v37
	v_cvt_pk_bf16_f32 v226, v36, v37
	v_exp_f32_e32 v40, v40
	v_exp_f32_e32 v41, v41
	v_add_f32_e32 v250, v250, v38
	v_add_f32_e32 v251, v251, v39
	v_cvt_pk_bf16_f32 v227, v38, v39
	v_exp_f32_e32 v42, v42
	v_exp_f32_e32 v43, v43
	v_add_f32_e32 v248, v248, v40
	v_add_f32_e32 v249, v249, v41
	v_cvt_pk_bf16_f32 v228, v40, v41
	v_exp_f32_e32 v44, v44
	v_exp_f32_e32 v45, v45
	v_add_f32_e32 v250, v250, v42
	v_add_f32_e32 v251, v251, v43
	v_cvt_pk_bf16_f32 v229, v42, v43
	v_exp_f32_e32 v46, v46
	v_exp_f32_e32 v47, v47
	v_add_f32_e32 v248, v248, v44
	v_add_f32_e32 v249, v249, v45
	v_cvt_pk_bf16_f32 v230, v44, v45
	v_add_f32_e32 v250, v250, v46
	v_add_f32_e32 v251, v251, v47
	v_cvt_pk_bf16_f32 v231, v46, v47
	v_add_f32_e32 v248, v248, v249
	v_add_f32_e32 v250, v250, v251
	v_add_f32_e32 v248, v248, v250
	v_add_f32_e32 v170, v170, v248
	s_branch .Lpagefit_2
	s_nop 0
	s_nop 0
	s_nop 0
	s_nop 0
	s_nop 0
	s_nop 0
	s_nop 0
	s_nop 0
	s_nop 0
	s_nop 0
	s_nop 0
	s_nop 0
	s_nop 0
	s_nop 0
	s_nop 0
	s_nop 0
	s_nop 0
	s_nop 0
	s_nop 0
	s_nop 0
	s_nop 0
	s_nop 0
	s_nop 0
	s_nop 0
	s_nop 0
	s_nop 0
	s_nop 0
	s_nop 0
	s_nop 0
	s_nop 0
	s_nop 0
	s_nop 0
	s_nop 0
	s_nop 0
	s_nop 0
	s_nop 0
	s_nop 0
	s_nop 0
	s_nop 0
	s_nop 0
	s_nop 0
	s_nop 0
	s_nop 0
	s_nop 0
	s_nop 0
	s_nop 0
	s_nop 0
	s_nop 0
	s_nop 0
	s_nop 0
	s_nop 0
	s_nop 0
	s_nop 0
	s_nop 0
	s_nop 0
	s_nop 0
	s_nop 0
	s_nop 0
	s_nop 0
	s_nop 0
	s_nop 0
	s_nop 0
	s_nop 0
	s_nop 0
	s_nop 0
	s_nop 0
	s_nop 0
	s_nop 0
	s_nop 0
	s_nop 0
	s_nop 0
	s_nop 0
	s_nop 0
	s_nop 0
	s_nop 0
	s_nop 0
	s_nop 0
	s_nop 0
	s_nop 0
	s_nop 0
	s_nop 0
	s_nop 0
	s_nop 0
	s_nop 0
	s_nop 0
	s_nop 0
	s_nop 0
	s_nop 0
	s_nop 0
	s_nop 0
	s_nop 0
	s_nop 0
	s_nop 0
	s_nop 0
	s_nop 0
	s_nop 0
	s_nop 0
	s_nop 0
	s_nop 0
	s_nop 0
	s_nop 0
	s_nop 0
	s_nop 0
	s_nop 0
	s_nop 0
	s_nop 0
	s_nop 0
	s_nop 0
	s_nop 0
	s_nop 0
	s_nop 0
	s_nop 0
	s_nop 0
	s_nop 0
	s_nop 0
	s_nop 0
	s_nop 0
	s_nop 0
	s_nop 0
	s_nop 0
	s_nop 0
	s_nop 0
	s_nop 0
	s_nop 0
	s_nop 0
	s_nop 0
	s_nop 0
	s_nop 0
	s_nop 0
	s_nop 0
	s_nop 0
	s_nop 0
	s_nop 0
	s_nop 0
	s_nop 0
	s_nop 0
	s_nop 0
	s_nop 0
	s_nop 0
	s_nop 0
	s_nop 0
	s_nop 0
	s_nop 0
	s_nop 0
	s_nop 0
	s_nop 0
	s_nop 0
	s_nop 0
	s_nop 0
	s_nop 0
	s_nop 0
	s_nop 0
	s_nop 0
	s_nop 0
	s_nop 0
	s_nop 0
	s_nop 0
	s_nop 0
	s_nop 0
	s_nop 0
	s_nop 0
	s_nop 0
	s_nop 0
	s_nop 0
	s_nop 0
	s_nop 0
	s_nop 0
	s_nop 0
	s_nop 0
	s_nop 0
	s_nop 0
	s_nop 0
	s_nop 0
	s_nop 0
	s_nop 0
	s_nop 0
	s_nop 0
	s_nop 0
	s_nop 0
	s_nop 0
	s_nop 0
	s_nop 0
	s_nop 0
	s_nop 0
	s_nop 0
	s_nop 0
	s_nop 0
	s_nop 0
	s_nop 0
	s_nop 0
	s_nop 0
	s_nop 0
	s_nop 0
	s_nop 0
	s_nop 0
	s_nop 0
	s_nop 0
	s_nop 0
	s_nop 0
	s_nop 0
	s_nop 0
	s_nop 0
	s_nop 0
	s_nop 0
	s_nop 0
	s_nop 0
	s_nop 0
	s_nop 0
	s_nop 0
	s_nop 0
	s_nop 0
	s_nop 0
	s_nop 0
	s_nop 0
	s_nop 0
	s_nop 0
	s_nop 0
	s_nop 0
	s_nop 0
	s_nop 0
	s_nop 0
	s_nop 0
	s_nop 0
	s_nop 0
	s_nop 0
	s_nop 0
	s_nop 0
	s_nop 0
	s_nop 0
	s_nop 0
	s_nop 0
	s_nop 0
	s_nop 0
	s_nop 0
	s_nop 0
	s_nop 0
	s_nop 0
	s_nop 0
	s_nop 0
	s_nop 0
	s_nop 0
	s_nop 0
	s_nop 0
	s_nop 0
	s_nop 0
	s_nop 0
	s_nop 0
	s_nop 0
	s_nop 0
	s_nop 0
	s_nop 0
	s_nop 0
	s_nop 0
	s_nop 0
	s_nop 0
	s_nop 0
	s_nop 0
	s_nop 0
	s_nop 0
	s_nop 0
	s_nop 0
	s_nop 0
	s_nop 0
	s_nop 0
	s_nop 0
	s_nop 0
	s_nop 0
	s_nop 0
	s_nop 0
	s_nop 0
	s_nop 0
	s_nop 0
	s_nop 0
	s_nop 0
	s_nop 0
	s_nop 0
	s_nop 0
	s_nop 0
	s_nop 0
	s_nop 0
	s_nop 0
	s_nop 0
	s_nop 0
	s_nop 0
	s_nop 0
	s_nop 0
	s_nop 0
	s_nop 0
	s_nop 0
; __device__ __forceinline__ float max2f(float a, float b) { float r; asm("v_max_f32_e32 %0, %1, %2" : "=v"(r) : "v"(a), "v"(b)); return r; }
; template <int GRP, bool has_next> __device__ __forceinline__ void att_step(const AttCtx<GRP>& C, AttState<GRP>& S, int s, f32x16& P0, f32x16& P1, f32x16& PN0, f32x16& PN1, u32x4& kreg, u32x4& preg, u32x4& vreg) {
;     ...
;         att_kfrag<GRP, 0, NK0>(C, (s + 1) & 1, kfa);
;     }
;     if (has_next) { PN0 = __builtin_amdgcn_mfma_f32_32x32x16_bf16(kfa[0], S.qr[0], (f32x16){}, 0, 0, 0); PN1 = __builtin_amdgcn_mfma_f32_32x32x16_bf16(kfa[1], S.qr[0], (f32x16){}, 0, 0, 0); }
;     if ((t & 7) == 0) {
;         float ma = max3f(P0[0], P0[1], P0[2]), mb = max3f(P0[3], P0[4], P0[5]), mc = max3f(P1[0], P1[1], P1[2]), md = max3f(P1[3], P1[4], P1[5]);
;         ma = max3f(ma, P0[6], P0[7]); mb = max3f(mb, P0[8], P0[9]); mc = max3f(mc, P1[6], P1[7]); md = max3f(md, P1[8], P1[9]);
;         ma = max3f(ma, P0[10], P0[11]); mb = max3f(mb, P0[12], P0[13]); mc = max3f(mc, P1[10], P1[11]); md = max3f(md, P1[12], P1[13]);
;         ma = max3f(ma, P0[14], P0[15]); mc = max3f(mc, P1[14], P1[15]); ma = max3f(ma, mb, mc); mb = md;
;         const float mx = xhalf_max(max2f(ma, mb));
;         const int up = __any(mx > THR), dn = (t == 0) ? __any(mx < -THR) : 0;
;         if (up | dn) {
;             const float dl = ceilf((t == 0) ? mx : fmaxf(mx, 0.f));
;             const float f = (t == 0) ? 0.f : __builtin_amdgcn_exp2f(-dl);
;             S.mhat += dl; S.lrun *= f;
; #pragma unroll
;             for (int r = 0; r < 16; ++r) { P0[r] -= dl; P1[r] -= dl; S.o0[r] *= f; S.o1[r] *= f; }
;             S.refnz = __any(S.mhat != 0.f);
;         }
;     }
;     __builtin_amdgcn_sched_barrier(0);
;     const unsigned mbits = (t == 63 || C.hi != 0) ? 0u : (__float_as_uint(-S.mhat) >> 16);
;     const u32x4 qxw = {mbits, 0u, 0u, 0u}; const bf16x8 qx = __builtin_bit_cast(bf16x8, qxw);
;     const bf16x8 ones = {0x3f80, 0x3f80, 0x3f80, 0x3f80, 0x3f80, 0x3f80, 0x3f80, 0x3f80};
;     constexpr int NE = NKS - 1;
;     float ra = 0.f, rb = 0.f, rc = 0.f, rd = 0.f;
;     ...
; #pragma unroll
;     for (int c = 1; c < NKS; ++c) {
;         if (has_next) {
;             if (c == NK0) att_kfrag<GRP, NK0, NK1>(C, (s + 1) & 1, kfb);
;             const bf16x8 a0 = c < NK0 ? kfa[2 * c] : kfb[2 * (c - NK0)], a1 = c < NK0 ? kfa[2 * c + 1] : kfb[2 * (c - NK0) + 1];
.Lpagefit_2:
.Lmla_L_loop:
	ds_read_b128 v[136:139], v174 offset:13312
	ds_read_b128 v[140:143], v174 offset:19968
	ds_read_b128 v[144:147], v174 offset:13344
	ds_read_b128 v[148:151], v174 offset:20000
	ds_read_b128 v[176:179], v174 offset:13376
	ds_read_b128 v[180:183], v174 offset:20032
	s_waitcnt lgkmcnt(5)
	v_mfma_f32_32x32x16_bf16 v[80:95], v[136:139], v[128:131], 0
	ds_read_b128 v[136:139], v174 offset:13408
	s_waitcnt lgkmcnt(5)
	v_mfma_f32_32x32x16_bf16 v[64:79], v[140:143], v[128:131], 0
	ds_read_b128 v[140:143], v174 offset:20064
	s_waitcnt lgkmcnt(5)
	v_mfma_f32_32x32x16_bf16 v[80:95], v[144:147], v[124:127], v[80:95]
	ds_read_b128 v[144:147], v174 offset:13440
	s_waitcnt lgkmcnt(5)
	v_mfma_f32_32x32x16_bf16 v[64:79], v[148:151], v[124:127], v[64:79]
	ds_read_b128 v[148:151], v174 offset:20096
	s_waitcnt lgkmcnt(5)
	v_mfma_f32_32x32x16_bf16 v[80:95], v[176:179], v[120:123], v[80:95]
	ds_read_b128 v[176:179], v174 offset:13472
	s_waitcnt lgkmcnt(5)
	v_mfma_f32_32x32x16_bf16 v[64:79], v[180:183], v[120:123], v[64:79]
	ds_read_b128 v[180:183], v174 offset:20128
	s_waitcnt lgkmcnt(5)
	v_mfma_f32_32x32x16_bf16 v[80:95], v[136:139], v[116:119], v[80:95]
	ds_read_b128 v[232:235], v157 offset:26624
	s_waitcnt lgkmcnt(5)
	v_mfma_f32_32x32x16_bf16 v[64:79], v[140:143], v[116:119], v[64:79]
	ds_read_b128 v[236:239], v157 offset:31232
	s_waitcnt lgkmcnt(5)
	v_mfma_f32_32x32x16_bf16 v[80:95], v[144:147], v[112:115], v[80:95]
	ds_read_b128 v[240:243], v157 offset:26656
	s_waitcnt lgkmcnt(5)
	v_mfma_f32_32x32x16_bf16 v[64:79], v[148:151], v[112:115], v[64:79]
	ds_read_b128 v[244:247], v157 offset:31264
	s_waitcnt lgkmcnt(5)
	v_mfma_f32_32x32x16_bf16 v[80:95], v[176:179], v[108:111], v[80:95]
	s_waitcnt lgkmcnt(4)
	v_mfma_f32_32x32x16_bf16 v[64:79], v[180:183], v[108:111], v[64:79]
	s_cmp_eq_u32 s72, 0
	s_cbranch_scc1 .Lmla_nrz3
	v_xor_b32_e32 v195, 0x80000000, v175
	s_mov_b32 s18, s16
	s_mov_b32 s19, s16
	s_mov_b32 s17, s16
	v_mov_b64_e32 v[186:187], s[18:19]
	v_mov_b64_e32 v[184:185], s[16:17]
	s_mov_b64 vcc, s[0:1]
	v_cndmask_b32_sdwa v96, v97, v195, vcc dst_sel:DWORD dst_unused:UNUSED_PAD src0_sel:DWORD src1_sel:WORD_1
	v_mov_b32_e32 v98, v97
	v_mov_b32_e32 v99, v97
	s_nop 1
	v_mfma_f32_32x32x16_bf16 v[80:95], v[184:187], v[96:99], v[80:95]
	v_mfma_f32_32x32x16_bf16 v[64:79], v[184:187], v[96:99], v[64:79]

;     __device__ __forceinline__ void mid(f32x4 (&acc)[2][2][4][2], const Unit& u, int wr, int fr) const {
;     ...
; #pragma unroll
;             for (int ai = 0; ai < 2; ++ai)
; #pragma unroll
;                 for (int m = 0; m < 4; ++m) { const int row = u.pm * BM + wr * 64 + fr + ai * HALF + m * 16; const f32x4 sq = *(const f32x4*)(rs2 + 4 * row); const float q = sqrtf(((sq[2] + sq[3]) * (1.f / 512.f) + NEPS) / ((sq[0] + sq[1]) * (1.f / 512.f) + NEPS));
; template <class Epi, class Sched, bool ALIGN_EPI = false, bool SP2 = false>
; __device__ __forceinline__ void gemm_phase(PG8_LAS unsigned char* lds, const Gemm g, const Sched S, const Epi E) {
;     ...
;         const bool has_next = S.next(ui + 1, nxt);
;         const char* nA = has_next ? (const char*)g.A + (size_t)nxt.pm * tstep : cA; const char* nB = has_next ? (const char*)g.Bt + (size_t)nxt.pn * tstep : cB;
;         for (int t = 0; t < nt; t += 2) {
;             if constexpr (Epi::MIDT >= 0) { if (t == Epi::MIDT) E.mid(acc, cur, wr, fr); }
;             const bool last = (t == nt - 2);
;             const char* a1 = cA + (size_t)(t + 1) * kstep;
;             const char* a2 = last ? nA : cA + (size_t)(t + 2) * kstep; const char* b2 = last ? nB : cB + (size_t)(t + 2) * kstep;
;             const char* a3 = a2 + kstep; const char* b3 = b2 + kstep;
.LBB0_897:
	s_ashr_i32 s51, s50, 31
	s_lshl_b64 s[10:11], s[50:51], 19
	s_add_u32 s52, s48, s10
	v_lshl_add_u32 v2, s64, 10, v171
	s_addc_u32 s53, s49, s11
	v_add_u32_e32 v4, 0x200, v2
	s_and_b64 s[10:11], s[0:1], exec
	v_ashrrev_i32_e32 v5, 31, v4
	s_cselect_b32 s51, s53, s67
	s_cselect_b32 s72, s52, s66
	s_ashr_i32 s45, s44, 31
	v_lshl_add_u64 v[130:131], v[4:5], 2, s[46:47]
	v_add_u32_e32 v4, 0x240, v2
	s_lshl_b64 s[10:11], s[44:45], 19
	v_readlane_b32 s14, v255, 34
	v_ashrrev_i32_e32 v3, 31, v2
	v_ashrrev_i32_e32 v5, 31, v4
	v_readlane_b32 s15, v255, 35
	s_add_u32 s62, s14, s10
	v_lshl_add_u64 v[128:129], v[2:3], 2, s[46:47]
	global_load_dwordx4 v[190:193], v[128:129], off
	global_load_dwordx4 v[194:197], v[128:129], off offset:256
	global_load_dwordx4 v[198:201], v[128:129], off offset:512
	global_load_dwordx4 v[202:205], v[128:129], off offset:768
	global_load_dwordx4 v[206:209], v[128:129], off offset:2048
	global_load_dwordx4 v[210:213], v[128:129], off offset:2304
	global_load_dwordx4 v[214:217], v[128:129], off offset:2560
	global_load_dwordx4 v[218:221], v[128:129], off offset:2816
	v_lshl_add_u64 v[132:133], v[4:5], 2, s[46:47]
	v_add_u32_e32 v4, 0x280, v2
	v_add_u32_e32 v2, 0x2c0, v2
	s_addc_u32 s63, s15, s11
	v_ashrrev_i32_e32 v3, 31, v2
	s_and_b64 s[10:11], s[0:1], exec
	v_ashrrev_i32_e32 v5, 31, v4
	v_lshl_add_u64 v[136:137], v[2:3], 2, s[46:47]
	v_mov_b32_e32 v2, v0
	v_mov_b32_e32 v3, v0
	s_cselect_b32 s45, s63, s7
	s_cselect_b32 s73, s62, s6
	v_lshl_add_u64 v[134:135], v[4:5], 2, s[46:47]
	s_add_u32 s74, s6, 0x100
	v_mov_b32_e32 v1, v0
	v_mov_b64_e32 v[6:7], v[2:3]
	v_mov_b64_e32 v[10:11], v[2:3]
	v_mov_b64_e32 v[22:23], v[2:3]
	v_mov_b64_e32 v[26:27], v[2:3]
	v_mov_b64_e32 v[38:39], v[2:3]
	v_mov_b64_e32 v[42:43], v[2:3]
	v_mov_b64_e32 v[54:55], v[2:3]
	v_mov_b64_e32 v[58:59], v[2:3]
	v_mov_b64_e32 v[14:15], v[2:3]
	v_mov_b64_e32 v[18:19], v[2:3]
	v_mov_b64_e32 v[30:31], v[2:3]
	v_mov_b64_e32 v[34:35], v[2:3]
	v_mov_b64_e32 v[46:47], v[2:3]
	v_mov_b64_e32 v[50:51], v[2:3]
	v_mov_b64_e32 v[62:63], v[2:3]
	v_mov_b64_e32 v[66:67], v[2:3]
	v_mov_b64_e32 v[70:71], v[2:3]
	v_mov_b64_e32 v[74:75], v[2:3]
	v_mov_b64_e32 v[86:87], v[2:3]
	v_mov_b64_e32 v[90:91], v[2:3]
	v_mov_b64_e32 v[102:103], v[2:3]
	v_mov_b64_e32 v[106:107], v[2:3]
	v_mov_b64_e32 v[118:119], v[2:3]
	v_mov_b64_e32 v[126:127], v[2:3]
	v_mov_b64_e32 v[78:79], v[2:3]
	v_mov_b64_e32 v[82:83], v[2:3]
	v_mov_b64_e32 v[94:95], v[2:3]
	v_mov_b64_e32 v[98:99], v[2:3]
	v_mov_b64_e32 v[110:111], v[2:3]
	v_mov_b64_e32 v[114:115], v[2:3]
	v_mov_b64_e32 v[142:143], v[2:3]
	v_mov_b64_e32 v[146:147], v[2:3]
	v_lshl_add_u64 v[138:139], s[66:67], 0, v[156:157]
	v_lshl_add_u64 v[164:165], s[66:67], 0, v[158:159]
	s_addc_u32 s75, s7, 0
	s_mov_b32 s76, -2
	s_mov_b64 s[70:71], 0
	v_mov_b64_e32 v[4:5], v[0:1]
	v_mov_b64_e32 v[8:9], v[0:1]
	v_mov_b64_e32 v[20:21], v[0:1]
	v_mov_b64_e32 v[24:25], v[0:1]
	v_mov_b64_e32 v[36:37], v[0:1]
	v_mov_b64_e32 v[40:41], v[0:1]
	v_mov_b64_e32 v[52:53], v[0:1]
	v_mov_b64_e32 v[56:57], v[0:1]
	v_mov_b64_e32 v[12:13], v[0:1]
	v_mov_b64_e32 v[16:17], v[0:1]
	v_mov_b64_e32 v[28:29], v[0:1]
	v_mov_b64_e32 v[32:33], v[0:1]
	v_mov_b64_e32 v[44:45], v[0:1]
	v_mov_b64_e32 v[48:49], v[0:1]
	v_mov_b64_e32 v[60:61], v[0:1]
	v_mov_b64_e32 v[64:65], v[0:1]
	v_mov_b64_e32 v[68:69], v[0:1]
	v_mov_b64_e32 v[72:73], v[0:1]
	v_mov_b64_e32 v[84:85], v[0:1]
	v_mov_b64_e32 v[88:89], v[0:1]
	v_mov_b64_e32 v[100:101], v[0:1]
	v_mov_b64_e32 v[104:105], v[0:1]
	v_mov_b64_e32 v[116:117], v[0:1]
	v_mov_b64_e32 v[124:125], v[0:1]
	v_mov_b64_e32 v[76:77], v[0:1]
	v_mov_b64_e32 v[80:81], v[0:1]
	v_mov_b64_e32 v[92:93], v[0:1]
	v_mov_b64_e32 v[96:97], v[0:1]
	v_mov_b64_e32 v[108:109], v[0:1]
	v_mov_b64_e32 v[112:113], v[0:1]
	v_mov_b64_e32 v[140:141], v[0:1]
	v_mov_b64_e32 v[144:145], v[0:1]
	v_mov_b32_e32 v236, s42
	s_waitcnt vmcnt(7)
	v_add_f32_e32 v222, v192, v193
	v_add_f32_e32 v223, v190, v191
	v_fma_f32 v222, v222, s40, v236
	v_fma_f32 v223, v223, s40, v236
	v_div_scale_f32 v224, s[82:83], v223, v223, v222
	v_rcp_f32_e32 v225, v224
	s_nop 0
	v_fma_f32 v226, -v224, v225, 1.0
	v_fmac_f32_e32 v225, v226, v225
	v_div_scale_f32 v227, vcc, v222, v223, v222
	v_mul_f32_e32 v228, v227, v225
	v_fma_f32 v229, -v224, v228, v227
	v_fmac_f32_e32 v228, v229, v225
	v_fma_f32 v224, -v224, v228, v227
	s_nop 0
	v_div_fmas_f32 v224, v224, v225, v228
	v_div_fixup_f32 v224, v224, v223, v222
	v_mul_f32_e32 v225, 0x4f800000, v224
	v_cmp_gt_f32_e64 s[78:79], s61, v224
	s_nop 1
	v_cndmask_b32_e64 v224, v224, v225, s[78:79]
	v_sqrt_f32_e32 v225, v224
	s_nop 0
	v_add_u32_e32 v226, -1, v225
	v_fma_f32 v227, -v226, v225, v224
	v_cmp_ge_f32_e64 s[80:81], 0, v227
	v_add_u32_e32 v228, 1, v225
	s_nop 0
	v_cndmask_b32_e64 v226, v225, v226, s[80:81]
	v_fma_f32 v227, -v228, v225, v224
	v_cmp_lt_f32_e64 s[80:81], 0, v227
	s_nop 1
	v_cndmask_b32_e64 v226, v226, v228, s[80:81]
	v_mul_f32_e32 v227, 0x37800000, v226
	v_cndmask_b32_e64 v226, v226, v227, s[78:79]
	v_cmp_class_f32_e32 vcc, v224, v172
	s_nop 1
	v_cndmask_b32_e32 v244, v226, v224, vcc
	s_waitcnt vmcnt(6)
;     __device__ __forceinline__ void mid(f32x4 (&acc)[2][2][4][2], const Unit& u, int wr, int fr) const {
;     ...
; #pragma unroll
;             for (int ai = 0; ai < 2; ++ai)
; #pragma unroll
;                 for (int m = 0; m < 4; ++m) { const int row = u.pm * BM + wr * 64 + fr + ai * HALF + m * 16; const f32x4 sq = *(const f32x4*)(rs2 + 4 * row); const float q = sqrtf(((sq[2] + sq[3]) * (1.f / 512.f) + NEPS) / ((sq[0] + sq[1]) * (1.f / 512.f) + NEPS));
	v_add_f32_e32 v222, v196, v197
	v_add_f32_e32 v223, v194, v195
	v_fma_f32 v222, v222, s40, v236
	v_fma_f32 v223, v223, s40, v236
	v_div_scale_f32 v224, s[82:83], v223, v223, v222
	v_rcp_f32_e32 v225, v224
	s_nop 0
	v_fma_f32 v226, -v224, v225, 1.0
	v_fmac_f32_e32 v225, v226, v225
	v_div_scale_f32 v227, vcc, v222, v223, v222
	v_mul_f32_e32 v228, v227, v225
	v_fma_f32 v229, -v224, v228, v227
	v_fmac_f32_e32 v228, v229, v225
	v_fma_f32 v224, -v224, v228, v227
	s_nop 0
	v_div_fmas_f32 v224, v224, v225, v228
	v_div_fixup_f32 v224, v224, v223, v222
	v_mul_f32_e32 v225, 0x4f800000, v224
	v_cmp_gt_f32_e64 s[78:79], s61, v224
	s_nop 1
	v_cndmask_b32_e64 v224, v224, v225, s[78:79]
	v_sqrt_f32_e32 v225, v224
	s_nop 0
	v_add_u32_e32 v226, -1, v225
	v_fma_f32 v227, -v226, v225, v224
	v_cmp_ge_f32_e64 s[80:81], 0, v227
	v_add_u32_e32 v228, 1, v225
	s_nop 0
	v_cndmask_b32_e64 v226, v225, v226, s[80:81]
	v_fma_f32 v227, -v228, v225, v224
	v_cmp_lt_f32_e64 s[80:81], 0, v227
	s_nop 1
	v_cndmask_b32_e64 v226, v226, v228, s[80:81]
	v_mul_f32_e32 v227, 0x37800000, v226
	v_cndmask_b32_e64 v226, v226, v227, s[78:79]
	v_cmp_class_f32_e32 vcc, v224, v172
	s_nop 1
	v_cndmask_b32_e32 v245, v226, v224, vcc
	s_waitcnt vmcnt(5)
	v_add_f32_e32 v222, v200, v201
	v_add_f32_e32 v223, v198, v199
	v_fma_f32 v222, v222, s40, v236
	v_fma_f32 v223, v223, s40, v236
	v_div_scale_f32 v224, s[82:83], v223, v223, v222
	v_rcp_f32_e32 v225, v224
	s_nop 0
	v_fma_f32 v226, -v224, v225, 1.0
	v_fmac_f32_e32 v225, v226, v225
	v_div_scale_f32 v227, vcc, v222, v223, v222
	v_mul_f32_e32 v228, v227, v225
	v_fma_f32 v229, -v224, v228, v227
	v_fmac_f32_e32 v228, v229, v225
	v_fma_f32 v224, -v224, v228, v227
	s_nop 0
	v_div_fmas_f32 v224, v224, v225, v228
	v_div_fixup_f32 v224, v224, v223, v222
	v_mul_f32_e32 v225, 0x4f800000, v224
	v_cmp_gt_f32_e64 s[78:79], s61, v224
	s_nop 1
	v_cndmask_b32_e64 v224, v224, v225, s[78:79]
	v_sqrt_f32_e32 v225, v224
	s_nop 0
	v_add_u32_e32 v226, -1, v225
	v_fma_f32 v227, -v226, v225, v224
	v_cmp_ge_f32_e64 s[80:81], 0, v227
	v_add_u32_e32 v228, 1, v225
	s_nop 0
	v_cndmask_b32_e64 v226, v225, v226, s[80:81]
	v_fma_f32 v227, -v228, v225, v224
	v_cmp_lt_f32_e64 s[80:81], 0, v227
	s_nop 1
	v_cndmask_b32_e64 v226, v226, v228, s[80:81]
	v_mul_f32_e32 v227, 0x37800000, v226
	v_cndmask_b32_e64 v226, v226, v227, s[78:79]
	v_cmp_class_f32_e32 vcc, v224, v172
	s_nop 1
	v_cndmask_b32_e32 v246, v226, v224, vcc
	s_waitcnt vmcnt(4)
	v_add_f32_e32 v222, v204, v205
	v_add_f32_e32 v223, v202, v203
	v_fma_f32 v222, v222, s40, v236
	v_fma_f32 v223, v223, s40, v236
	v_div_scale_f32 v224, s[82:83], v223, v223, v222
	v_rcp_f32_e32 v225, v224
	s_nop 0
	v_fma_f32 v226, -v224, v225, 1.0
	v_fmac_f32_e32 v225, v226, v225
	v_div_scale_f32 v227, vcc, v222, v223, v222
	v_mul_f32_e32 v228, v227, v225
	v_fma_f32 v229, -v224, v228, v227
	v_fmac_f32_e32 v228, v229, v225
	v_fma_f32 v224, -v224, v228, v227
	s_nop 0
	v_div_fmas_f32 v224, v224, v225, v228
	v_div_fixup_f32 v224, v224, v223, v222
	v_mul_f32_e32 v225, 0x4f800000, v224
	v_cmp_gt_f32_e64 s[78:79], s61, v224
	s_nop 1
	v_cndmask_b32_e64 v224, v224, v225, s[78:79]
	v_sqrt_f32_e32 v225, v224
	s_nop 0
	v_add_u32_e32 v226, -1, v225
	v_fma_f32 v227, -v226, v225, v224
	v_cmp_ge_f32_e64 s[80:81], 0, v227
	v_add_u32_e32 v228, 1, v225
	s_nop 0
	v_cndmask_b32_e64 v226, v225, v226, s[80:81]
	v_fma_f32 v227, -v228, v225, v224
	v_cmp_lt_f32_e64 s[80:81], 0, v227
	s_nop 1
	v_cndmask_b32_e64 v226, v226, v228, s[80:81]
	v_mul_f32_e32 v227, 0x37800000, v226
	v_cndmask_b32_e64 v226, v226, v227, s[78:79]
	v_cmp_class_f32_e32 vcc, v224, v172
	s_nop 1
	v_cndmask_b32_e32 v247, v226, v224, vcc
	s_waitcnt vmcnt(3)
	v_add_f32_e32 v222, v208, v209
	v_add_f32_e32 v223, v206, v207
	v_fma_f32 v222, v222, s40, v236
	v_fma_f32 v223, v223, s40, v236
	v_div_scale_f32 v224, s[82:83], v223, v223, v222
	v_rcp_f32_e32 v225, v224
	s_nop 0
	v_fma_f32 v226, -v224, v225, 1.0
	v_fmac_f32_e32 v225, v226, v225
	v_div_scale_f32 v227, vcc, v222, v223, v222
	v_mul_f32_e32 v228, v227, v225
	v_fma_f32 v229, -v224, v228, v227
	v_fmac_f32_e32 v228, v229, v225
	v_fma_f32 v224, -v224, v228, v227
	s_nop 0
	v_div_fmas_f32 v224, v224, v225, v228
	v_div_fixup_f32 v224, v224, v223, v222
	v_mul_f32_e32 v225, 0x4f800000, v224
	v_cmp_gt_f32_e64 s[78:79], s61, v224
	s_nop 1
	v_cndmask_b32_e64 v224, v224, v225, s[78:79]
	v_sqrt_f32_e32 v225, v224
	s_nop 0
	v_add_u32_e32 v226, -1, v225
	v_fma_f32 v227, -v226, v225, v224
	v_cmp_ge_f32_e64 s[80:81], 0, v227
	v_add_u32_e32 v228, 1, v225
	s_nop 0
	v_cndmask_b32_e64 v226, v225, v226, s[80:81]
	v_fma_f32 v227, -v228, v225, v224
	v_cmp_lt_f32_e64 s[80:81], 0, v227
	s_nop 1
	v_cndmask_b32_e64 v226, v226, v228, s[80:81]
	v_mul_f32_e32 v227, 0x37800000, v226
	v_cndmask_b32_e64 v226, v226, v227, s[78:79]
	v_cmp_class_f32_e32 vcc, v224, v172
	s_nop 1
	v_cndmask_b32_e32 v248, v226, v224, vcc
	s_waitcnt vmcnt(2)
;     __device__ __forceinline__ void mid(f32x4 (&acc)[2][2][4][2], const Unit& u, int wr, int fr) const {
;     ...
; #pragma unroll
;             for (int ai = 0; ai < 2; ++ai)
; #pragma unroll
;                 for (int m = 0; m < 4; ++m) { const int row = u.pm * BM + wr * 64 + fr + ai * HALF + m * 16; const f32x4 sq = *(const f32x4*)(rs2 + 4 * row); const float q = sqrtf(((sq[2] + sq[3]) * (1.f / 512.f) + NEPS) / ((sq[0] + sq[1]) * (1.f / 512.f) + NEPS));
	v_add_f32_e32 v222, v212, v213
	v_add_f32_e32 v223, v210, v211
	v_fma_f32 v222, v222, s40, v236
	v_fma_f32 v223, v223, s40, v236
	v_div_scale_f32 v224, s[82:83], v223, v223, v222
	v_rcp_f32_e32 v225, v224
	s_nop 0
	v_fma_f32 v226, -v224, v225, 1.0
	v_fmac_f32_e32 v225, v226, v225
	v_div_scale_f32 v227, vcc, v222, v223, v222
	v_mul_f32_e32 v228, v227, v225
	v_fma_f32 v229, -v224, v228, v227
	v_fmac_f32_e32 v228, v229, v225
	v_fma_f32 v224, -v224, v228, v227
	s_nop 0
	v_div_fmas_f32 v224, v224, v225, v228
	v_div_fixup_f32 v224, v224, v223, v222
	v_mul_f32_e32 v225, 0x4f800000, v224
	v_cmp_gt_f32_e64 s[78:79], s61, v224
	s_nop 1
	v_cndmask_b32_e64 v224, v224, v225, s[78:79]
	v_sqrt_f32_e32 v225, v224
	s_nop 0
	v_add_u32_e32 v226, -1, v225
	v_fma_f32 v227, -v226, v225, v224
	v_cmp_ge_f32_e64 s[80:81], 0, v227
	v_add_u32_e32 v228, 1, v225
	s_nop 0
	v_cndmask_b32_e64 v226, v225, v226, s[80:81]
	v_fma_f32 v227, -v228, v225, v224
	v_cmp_lt_f32_e64 s[80:81], 0, v227
	s_nop 1
	v_cndmask_b32_e64 v226, v226, v228, s[80:81]
	v_mul_f32_e32 v227, 0x37800000, v226
	v_cndmask_b32_e64 v226, v226, v227, s[78:79]
	v_cmp_class_f32_e32 vcc, v224, v172
	s_nop 1
	v_cndmask_b32_e32 v249, v226, v224, vcc
	s_waitcnt vmcnt(1)
	v_add_f32_e32 v222, v216, v217
	v_add_f32_e32 v223, v214, v215
	v_fma_f32 v222, v222, s40, v236
	v_fma_f32 v223, v223, s40, v236
	v_div_scale_f32 v224, s[82:83], v223, v223, v222
	v_rcp_f32_e32 v225, v224
	s_nop 0
	v_fma_f32 v226, -v224, v225, 1.0
	v_fmac_f32_e32 v225, v226, v225
	v_div_scale_f32 v227, vcc, v222, v223, v222
	v_mul_f32_e32 v228, v227, v225
	v_fma_f32 v229, -v224, v228, v227
	v_fmac_f32_e32 v228, v229, v225
	v_fma_f32 v224, -v224, v228, v227
	s_nop 0
	v_div_fmas_f32 v224, v224, v225, v228
	v_div_fixup_f32 v224, v224, v223, v222
	v_mul_f32_e32 v225, 0x4f800000, v224
	v_cmp_gt_f32_e64 s[78:79], s61, v224
	s_nop 1
	v_cndmask_b32_e64 v224, v224, v225, s[78:79]
	v_sqrt_f32_e32 v225, v224
	s_nop 0
	v_add_u32_e32 v226, -1, v225
	v_fma_f32 v227, -v226, v225, v224
	v_cmp_ge_f32_e64 s[80:81], 0, v227
	v_add_u32_e32 v228, 1, v225
	s_nop 0
	v_cndmask_b32_e64 v226, v225, v226, s[80:81]
	v_fma_f32 v227, -v228, v225, v224
	v_cmp_lt_f32_e64 s[80:81], 0, v227
	s_nop 1
	v_cndmask_b32_e64 v226, v226, v228, s[80:81]
	v_mul_f32_e32 v227, 0x37800000, v226
	v_cndmask_b32_e64 v226, v226, v227, s[78:79]
	v_cmp_class_f32_e32 vcc, v224, v172
	s_nop 1
	v_cndmask_b32_e32 v250, v226, v224, vcc
	s_waitcnt vmcnt(0)
	v_add_f32_e32 v222, v220, v221
	v_add_f32_e32 v223, v218, v219
	v_fma_f32 v222, v222, s40, v236
	v_fma_f32 v223, v223, s40, v236
	v_div_scale_f32 v224, s[82:83], v223, v223, v222
	v_rcp_f32_e32 v225, v224
	s_nop 0
	v_fma_f32 v226, -v224, v225, 1.0
	v_fmac_f32_e32 v225, v226, v225
	v_div_scale_f32 v227, vcc, v222, v223, v222
	v_mul_f32_e32 v228, v227, v225
	v_fma_f32 v229, -v224, v228, v227
	v_fmac_f32_e32 v228, v229, v225
	v_fma_f32 v224, -v224, v228, v227
	s_nop 0
	v_div_fmas_f32 v224, v224, v225, v228
	v_div_fixup_f32 v224, v224, v223, v222
	v_mul_f32_e32 v225, 0x4f800000, v224
	v_cmp_gt_f32_e64 s[78:79], s61, v224
	s_nop 1
	v_cndmask_b32_e64 v224, v224, v225, s[78:79]
	v_sqrt_f32_e32 v225, v224
	s_nop 0
	v_add_u32_e32 v226, -1, v225
	v_fma_f32 v227, -v226, v225, v224
	v_cmp_ge_f32_e64 s[80:81], 0, v227
	v_add_u32_e32 v228, 1, v225
	s_nop 0
	v_cndmask_b32_e64 v226, v225, v226, s[80:81]
	v_fma_f32 v227, -v228, v225, v224
	v_cmp_lt_f32_e64 s[80:81], 0, v227
	s_nop 1
	v_cndmask_b32_e64 v226, v226, v228, s[80:81]
	v_mul_f32_e32 v227, 0x37800000, v226
	v_cndmask_b32_e64 v226, v226, v227, s[78:79]
	v_cmp_class_f32_e32 vcc, v224, v172
	s_nop 1
	v_cndmask_b32_e32 v251, v226, v224, vcc
	s_branch .LBB0_899
	s_branch .Lpagefit_5
	s_nop 0
	s_nop 0
	s_nop 0
	s_nop 0
	s_nop 0
	s_nop 0
	s_nop 0
	s_nop 0
	s_nop 0
	s_nop 0
	s_nop 0
	s_nop 0
	s_nop 0
	s_nop 0
	s_nop 0
	s_nop 0
	s_nop 0
	s_nop 0
	s_nop 0
	s_nop 0
	s_nop 0
	s_nop 0
	s_nop 0
	s_nop 0
	s_nop 0
	s_nop 0
	s_nop 0
	s_nop 0
	s_nop 0
	s_nop 0
	s_nop 0
	s_nop 0
	s_nop 0
	s_nop 0
	s_nop 0
	s_nop 0
	s_nop 0
	s_nop 0
	s_nop 0
	s_nop 0
	s_nop 0
	s_nop 0
	s_nop 0
	s_nop 0
	s_nop 0
	s_nop 0
	s_nop 0
	s_nop 0
	s_nop 0
	s_nop 0
	s_nop 0
	s_nop 0
	s_nop 0
	s_nop 0
	s_nop 0
	s_nop 0
	s_nop 0
	s_nop 0
	s_nop 0
	s_nop 0
	s_nop 0
	s_nop 0
	s_nop 0
	s_nop 0
	s_nop 0
	s_nop 0
	s_nop 0
	s_nop 0
	s_nop 0
	s_nop 0
	s_nop 0

;     __device__ __forceinline__ void mid(f32x4 (&acc)[2][2][4][2], const Unit& u, int wr, int fr) const {
;         if constexpr (MIX) {
; #pragma unroll
;             for (int ai = 0; ai < 2; ++ai)
; #pragma unroll
;                 for (int m = 0; m < 4; ++m) { const int row = u.pm * BM + wr * 64 + fr + ai * HALF + m * 16; const f32x4 sq = *(const f32x4*)(rs2 + 4 * row); const float q = sqrtf(((sq[2] + sq[3]) * (1.f / 512.f) + NEPS) / ((sq[0] + sq[1]) * (1.f / 512.f) + NEPS));
; #pragma unroll
;                     for (int bj = 0; bj < 2; ++bj)
; #pragma unroll
;                         for (int n = 0; n < 2; ++n) acc[ai][bj][m][n] *= q; }
;         }
;     }
; template <class Epi, class Sched, bool ALIGN_EPI = false, bool SP2 = false>
; __device__ __forceinline__ void gemm_phase(PG8_LAS unsigned char* lds, const Gemm g, const Sched S, const Epi E) {
;     ...
;             if constexpr (Epi::MIDT >= 0) { if (t == Epi::MIDT) E.mid(acc, cur, wr, fr); }
.LBB0_899:
	s_cmpk_lg_i32 s70, 0x400
	s_cbranch_scc1 .LBB0_898
	s_nop 7
	s_nop 7
	v_pk_mul_f32 v[146:147], v[146:147], v[244:245] op_sel_hi:[1,0]
	v_pk_mul_f32 v[144:145], v[144:145], v[244:245] op_sel_hi:[1,0]
	v_pk_mul_f32 v[142:143], v[142:143], v[244:245] op_sel_hi:[1,0]
	v_pk_mul_f32 v[140:141], v[140:141], v[244:245] op_sel_hi:[1,0]
	v_pk_mul_f32 v[126:127], v[126:127], v[244:245] op_sel_hi:[1,0]
	v_pk_mul_f32 v[124:125], v[124:125], v[244:245] op_sel_hi:[1,0]
	v_pk_mul_f32 v[118:119], v[118:119], v[244:245] op_sel_hi:[1,0]
	v_pk_mul_f32 v[116:117], v[116:117], v[244:245] op_sel_hi:[1,0]
	v_pk_mul_f32 v[114:115], v[114:115], v[244:245] op_sel:[0,1]
	v_pk_mul_f32 v[112:113], v[112:113], v[244:245] op_sel:[0,1]
	v_pk_mul_f32 v[110:111], v[110:111], v[244:245] op_sel:[0,1]
	v_pk_mul_f32 v[108:109], v[108:109], v[244:245] op_sel:[0,1]
	v_pk_mul_f32 v[106:107], v[106:107], v[244:245] op_sel:[0,1]
	v_pk_mul_f32 v[104:105], v[104:105], v[244:245] op_sel:[0,1]
	v_pk_mul_f32 v[102:103], v[102:103], v[244:245] op_sel:[0,1]
	v_pk_mul_f32 v[100:101], v[100:101], v[244:245] op_sel:[0,1]
	v_pk_mul_f32 v[98:99], v[98:99], v[246:247] op_sel_hi:[1,0]
	v_pk_mul_f32 v[96:97], v[96:97], v[246:247] op_sel_hi:[1,0]
	v_pk_mul_f32 v[94:95], v[94:95], v[246:247] op_sel_hi:[1,0]
	v_pk_mul_f32 v[92:93], v[92:93], v[246:247] op_sel_hi:[1,0]
	v_pk_mul_f32 v[90:91], v[90:91], v[246:247] op_sel_hi:[1,0]
	v_pk_mul_f32 v[88:89], v[88:89], v[246:247] op_sel_hi:[1,0]
	v_pk_mul_f32 v[86:87], v[86:87], v[246:247] op_sel_hi:[1,0]
	v_pk_mul_f32 v[84:85], v[84:85], v[246:247] op_sel_hi:[1,0]
	v_pk_mul_f32 v[82:83], v[82:83], v[246:247] op_sel:[0,1]
	v_pk_mul_f32 v[80:81], v[80:81], v[246:247] op_sel:[0,1]
	v_pk_mul_f32 v[78:79], v[78:79], v[246:247] op_sel:[0,1]
	v_pk_mul_f32 v[76:77], v[76:77], v[246:247] op_sel:[0,1]
	v_pk_mul_f32 v[74:75], v[74:75], v[246:247] op_sel:[0,1]
	v_pk_mul_f32 v[72:73], v[72:73], v[246:247] op_sel:[0,1]
	v_pk_mul_f32 v[70:71], v[70:71], v[246:247] op_sel:[0,1]
	v_pk_mul_f32 v[68:69], v[68:69], v[246:247] op_sel:[0,1]
	v_pk_mul_f32 v[66:67], v[66:67], v[248:249] op_sel_hi:[1,0]
	v_pk_mul_f32 v[64:65], v[64:65], v[248:249] op_sel_hi:[1,0]
	v_pk_mul_f32 v[62:63], v[62:63], v[248:249] op_sel_hi:[1,0]
	v_pk_mul_f32 v[60:61], v[60:61], v[248:249] op_sel_hi:[1,0]
	v_pk_mul_f32 v[58:59], v[58:59], v[248:249] op_sel_hi:[1,0]
	v_pk_mul_f32 v[56:57], v[56:57], v[248:249] op_sel_hi:[1,0]
	v_pk_mul_f32 v[54:55], v[54:55], v[248:249] op_sel_hi:[1,0]
	v_pk_mul_f32 v[52:53], v[52:53], v[248:249] op_sel_hi:[1,0]
	v_pk_mul_f32 v[50:51], v[50:51], v[248:249] op_sel:[0,1]
	v_pk_mul_f32 v[48:49], v[48:49], v[248:249] op_sel:[0,1]
	v_pk_mul_f32 v[46:47], v[46:47], v[248:249] op_sel:[0,1]
	v_pk_mul_f32 v[44:45], v[44:45], v[248:249] op_sel:[0,1]
	v_pk_mul_f32 v[42:43], v[42:43], v[248:249] op_sel:[0,1]
	v_pk_mul_f32 v[40:41], v[40:41], v[248:249] op_sel:[0,1]
	v_pk_mul_f32 v[38:39], v[38:39], v[248:249] op_sel:[0,1]
	v_pk_mul_f32 v[36:37], v[36:37], v[248:249] op_sel:[0,1]
	v_pk_mul_f32 v[34:35], v[34:35], v[250:251] op_sel_hi:[1,0]
	v_pk_mul_f32 v[32:33], v[32:33], v[250:251] op_sel_hi:[1,0]
	v_pk_mul_f32 v[30:31], v[30:31], v[250:251] op_sel_hi:[1,0]
	v_pk_mul_f32 v[28:29], v[28:29], v[250:251] op_sel_hi:[1,0]
	v_pk_mul_f32 v[26:27], v[26:27], v[250:251] op_sel_hi:[1,0]
	v_pk_mul_f32 v[24:25], v[24:25], v[250:251] op_sel_hi:[1,0]
	v_pk_mul_f32 v[22:23], v[22:23], v[250:251] op_sel_hi:[1,0]
	v_pk_mul_f32 v[20:21], v[20:21], v[250:251] op_sel_hi:[1,0]
	v_pk_mul_f32 v[18:19], v[18:19], v[250:251] op_sel:[0,1]
	v_pk_mul_f32 v[16:17], v[16:17], v[250:251] op_sel:[0,1]
	v_pk_mul_f32 v[14:15], v[14:15], v[250:251] op_sel:[0,1]
	v_pk_mul_f32 v[12:13], v[12:13], v[250:251] op_sel:[0,1]
	v_pk_mul_f32 v[10:11], v[10:11], v[250:251] op_sel:[0,1]
	v_pk_mul_f32 v[8:9], v[8:9], v[250:251] op_sel:[0,1]
	v_pk_mul_f32 v[6:7], v[6:7], v[250:251] op_sel:[0,1]
	v_pk_mul_f32 v[4:5], v[4:5], v[250:251] op_sel:[0,1]
	s_branch .LBB0_898

; template <class Epi, class Sched, bool ALIGN_EPI = false, bool SP2 = false>
; __device__ __forceinline__ void gemm_phase(PG8_LAS unsigned char* lds, const Gemm g, const Sched S, const Epi E) {
;     ...
; #pragma unroll
;     for (int a = 0; a < 2; ++a)
; #pragma unroll
;         for (int b = 0; b < 2; ++b)
; #pragma unroll
;             for (int m = 0; m < 4; ++m)
; #pragma unroll
;                 for (int n = 0; n < 2; ++n) acc[a][b][m][n] = (f32x4){0.f, 0.f, 0.f, 0.f};
;     bf16x8 At[4][2], B0[2][2], B1[2][2];
;     const char* cA = (const char*)g.A + (size_t)cur.pm * tstep; const char* cB = (const char*)g.Bt + (size_t)cur.pn * tstep;
;     ...
;         const bool has_next = S.next(ui + 1, nxt);
;         const char* nA = has_next ? (const char*)g.A + (size_t)nxt.pm * tstep : cA; const char* nB = has_next ? (const char*)g.Bt + (size_t)nxt.pn * tstep : cB;
;         for (int t = 0; t < nt; t += 2) {
;             if constexpr (Epi::MIDT >= 0) { if (t == Epi::MIDT) E.mid(acc, cur, wr, fr); }
;             const bool last = (t == nt - 2);
;             const char* a1 = cA + (size_t)(t + 1) * kstep;
;             const char* a2 = last ? nA : cA + (size_t)(t + 2) * kstep; const char* b2 = last ? nB : cB + (size_t)(t + 2) * kstep;
;             const char* a3 = a2 + kstep; const char* b3 = b2 + kstep;
.LBB0_1024:
	s_ashr_i32 s19, s18, 31
	s_lshl_b64 s[20:21], s[18:19], 19
	s_add_u32 s20, s56, s20
	s_addc_u32 s21, s57, s21
	s_and_b64 s[36:37], s[0:1], exec
	s_cselect_b32 s19, s21, s41
	s_cselect_b32 s59, s20, s40
	s_ashr_i32 s17, s16, 31
	s_lshl_b64 s[36:37], s[16:17], 19
	s_add_u32 s36, s34, s36
	s_addc_u32 s37, s35, s37
	s_and_b64 s[44:45], s[0:1], exec
	s_cselect_b32 s17, s37, s43
	s_cselect_b32 s60, s36, s42
	s_add_u32 s40, s40, 0x40080
	s_addc_u32 s41, s41, 0
	s_add_u32 s61, s42, 0x100
	v_mov_b32_e32 v0, 0
	s_addc_u32 s62, s43, 0
	s_mov_b32 s63, -2
	v_mov_b32_e32 v1, v0
	v_mov_b32_e32 v2, v0
	v_mov_b32_e32 v3, v0
	v_mov_b32_e32 v8, v0
	v_mov_b32_e32 v9, v0
	v_mov_b32_e32 v10, v0
	v_mov_b32_e32 v11, v0
	v_mov_b32_e32 v16, v0
	v_mov_b32_e32 v17, v0
	v_mov_b32_e32 v18, v0
	v_mov_b32_e32 v19, v0
	v_mov_b32_e32 v24, v0
	v_mov_b32_e32 v25, v0
	v_mov_b32_e32 v26, v0
	v_mov_b32_e32 v27, v0
	v_mov_b32_e32 v32, v0
	v_mov_b32_e32 v33, v0
	v_mov_b32_e32 v34, v0
	v_mov_b32_e32 v35, v0
	v_mov_b32_e32 v40, v0
	v_mov_b32_e32 v41, v0
	v_mov_b32_e32 v42, v0
	v_mov_b32_e32 v43, v0
	v_mov_b32_e32 v48, v0
	v_mov_b32_e32 v49, v0
	v_mov_b32_e32 v50, v0
	v_mov_b32_e32 v51, v0
	v_mov_b32_e32 v56, v0
	v_mov_b32_e32 v57, v0
	v_mov_b32_e32 v58, v0
	v_mov_b32_e32 v59, v0
	v_mov_b32_e32 v4, v0
	v_mov_b32_e32 v5, v0
	v_mov_b32_e32 v6, v0
	v_mov_b32_e32 v7, v0
	v_mov_b32_e32 v12, v0
	v_mov_b32_e32 v13, v0
	v_mov_b32_e32 v14, v0
	v_mov_b32_e32 v15, v0
	v_mov_b32_e32 v20, v0
	v_mov_b32_e32 v21, v0
	v_mov_b32_e32 v22, v0
	v_mov_b32_e32 v23, v0
	v_mov_b32_e32 v28, v0
	v_mov_b32_e32 v29, v0
	v_mov_b32_e32 v30, v0
	v_mov_b32_e32 v31, v0
	v_mov_b32_e32 v36, v0
	v_mov_b32_e32 v37, v0
	v_mov_b32_e32 v38, v0
	v_mov_b32_e32 v39, v0
	v_mov_b32_e32 v44, v0
	v_mov_b32_e32 v45, v0
	v_mov_b32_e32 v46, v0
	v_mov_b32_e32 v47, v0
	v_mov_b32_e32 v52, v0
	v_mov_b32_e32 v53, v0
	v_mov_b32_e32 v54, v0
	v_mov_b32_e32 v55, v0
	v_mov_b32_e32 v60, v0
	v_mov_b32_e32 v61, v0
	v_mov_b32_e32 v62, v0
	v_mov_b32_e32 v63, v0
	v_mov_b32_e32 v64, v0
	v_mov_b32_e32 v65, v0
	v_mov_b32_e32 v66, v0
	v_mov_b32_e32 v67, v0
	v_mov_b32_e32 v72, v0
	v_mov_b32_e32 v73, v0
	v_mov_b32_e32 v74, v0
	v_mov_b32_e32 v75, v0
	v_mov_b32_e32 v80, v0
	v_mov_b32_e32 v81, v0
	v_mov_b32_e32 v82, v0
	v_mov_b32_e32 v83, v0
	v_mov_b32_e32 v88, v0
	v_mov_b32_e32 v89, v0
	v_mov_b32_e32 v90, v0
	v_mov_b32_e32 v91, v0
	v_mov_b32_e32 v96, v0
	v_mov_b32_e32 v97, v0
	v_mov_b32_e32 v98, v0
	v_mov_b32_e32 v99, v0
	v_mov_b32_e32 v104, v0
	v_mov_b32_e32 v105, v0
	v_mov_b32_e32 v106, v0
	v_mov_b32_e32 v107, v0
	v_mov_b32_e32 v112, v0
	v_mov_b32_e32 v113, v0
	v_mov_b32_e32 v114, v0
	v_mov_b32_e32 v115, v0
	v_mov_b32_e32 v120, v0
	v_mov_b32_e32 v121, v0
	v_mov_b32_e32 v122, v0
	v_mov_b32_e32 v123, v0
	v_mov_b32_e32 v68, v0
	v_mov_b32_e32 v69, v0
	v_mov_b32_e32 v70, v0
	v_mov_b32_e32 v71, v0
	v_mov_b32_e32 v76, v0
	v_mov_b32_e32 v77, v0
	v_mov_b32_e32 v78, v0
	v_mov_b32_e32 v79, v0
	v_mov_b32_e32 v84, v0
	v_mov_b32_e32 v85, v0
	v_mov_b32_e32 v86, v0
	v_mov_b32_e32 v87, v0
	v_mov_b32_e32 v92, v0
	v_mov_b32_e32 v93, v0
	v_mov_b32_e32 v94, v0
	v_mov_b32_e32 v95, v0
	v_mov_b32_e32 v100, v0
	v_mov_b32_e32 v101, v0
	v_mov_b32_e32 v102, v0
	v_mov_b32_e32 v103, v0
	v_mov_b32_e32 v108, v0
	v_mov_b32_e32 v109, v0
	v_mov_b32_e32 v110, v0
	v_mov_b32_e32 v111, v0
	v_mov_b32_e32 v116, v0
	v_mov_b32_e32 v117, v0
	v_mov_b32_e32 v118, v0
	v_mov_b32_e32 v119, v0
	v_mov_b32_e32 v124, v0
	v_mov_b32_e32 v125, v0
	v_mov_b32_e32 v126, v0
	v_mov_b32_e32 v127, v0
	s_branch .Lpagefit_6
	s_nop 0
	s_nop 0
	s_nop 0
	s_nop 0
	s_nop 0
	s_nop 0
	s_nop 0
	s_nop 0
	s_nop 0
	s_nop 0
	s_nop 0
	s_nop 0
	s_nop 0
	s_nop 0
	s_nop 0
	s_nop 0
	s_nop 0
	s_nop 0
	s_nop 0
	s_nop 0
	s_nop 0
	s_nop 0
	s_nop 0
	s_nop 0
	s_nop 0
	s_nop 0
	s_nop 0
	s_nop 0
	s_nop 0
	s_nop 0
	s_nop 0
	s_nop 0
	s_nop 0
	s_nop 0
	s_nop 0
	s_nop 0
	s_nop 0
	s_nop 0
	s_nop 0
	s_nop 0
	s_nop 0
	s_nop 0
	s_nop 0
	s_nop 0
	s_nop 0
	s_nop 0
	s_nop 0
	s_nop 0
	s_nop 0
	s_nop 0
	s_nop 0
	s_nop 0
	s_nop 0
	s_nop 0
	s_nop 0
	s_nop 0
	s_nop 0
	s_nop 0
	s_nop 0
	s_nop 0
	s_nop 0
	s_nop 0
	s_nop 0
	s_nop 0
	s_nop 0
	s_nop 0
	s_nop 0
	s_nop 0
	s_nop 0
	s_nop 0
	s_nop 0
	s_nop 0
	s_nop 0
	s_nop 0
	s_nop 0
	s_nop 0
	s_nop 0
	s_nop 0
	s_nop 0
	s_nop 0
	s_nop 0
	s_nop 0
	s_nop 0
	s_nop 0
	s_nop 0
	s_nop 0
	s_nop 0
	s_nop 0
	s_nop 0
	s_nop 0
	s_nop 0
	s_nop 0
	s_nop 0
	s_nop 0
	s_nop 0
	s_nop 0
	s_nop 0
	s_nop 0
	s_nop 0
	s_nop 0
	s_nop 0
	s_nop 0
	s_nop 0
	s_nop 0
	s_nop 0
	s_nop 0
	s_nop 0
	s_nop 0
	s_nop 0
	s_nop 0
	s_nop 0
	s_nop 0
	s_nop 0
	s_nop 0
	s_nop 0
	s_nop 0
	s_nop 0
	s_nop 0
	s_nop 0
	s_nop 0
	s_nop 0
	s_nop 0
	s_nop 0
	s_nop 0
	s_nop 0
	s_nop 0
	s_nop 0
	s_nop 0
	s_nop 0
	s_nop 0
	s_nop 0
	s_nop 0
	s_nop 0
	s_nop 0
	s_nop 0
	s_nop 0
	s_nop 0
	s_nop 0
	s_nop 0
	s_nop 0
	s_nop 0
	s_nop 0
	s_nop 0
	s_nop 0
	s_nop 0
	s_nop 0
	s_nop 0
	s_nop 0
	s_nop 0
	s_nop 0
	s_nop 0
	s_nop 0
	s_nop 0
	s_nop 0
	s_nop 0
	s_nop 0
	s_nop 0
	s_nop 0
	s_nop 0
	s_nop 0
	s_nop 0
	s_nop 0
	s_nop 0
	s_nop 0
	s_nop 0
	s_nop 0
	s_nop 0
	s_nop 0
	s_nop 0
	s_nop 0
	s_nop 0
	s_nop 0
	s_nop 0
	s_nop 0
	s_nop 0
	s_nop 0
	s_nop 0
	s_nop 0
	s_nop 0
	s_nop 0
	s_nop 0
	s_nop 0
	s_nop 0
	s_nop 0
	s_nop 0
	s_nop 0
	s_nop 0
	s_nop 0
	s_nop 0
	s_nop 0
	s_nop 0
	s_nop 0
	s_nop 0
; #define PG8_STAGE(bufoff, gbase, voff) do { _Pragma("unroll") for (int _i = 0; _i < 2; ++_i) \
;         __builtin_amdgcn_global_load_lds((const unsigned*)((const char*)(gbase) + (voff)[_i]), (PG8_LAS unsigned*)(lds + (bufoff) + ldsw + _i * 8192), 16, 0, 0); } while (0)
; #define PG8_LDA(dst, b, h) do { _Pragma("unroll") for (int m = 0; m < 4; ++m) _Pragma("unroll") for (int k = 0; k < 2; ++k) dst[m][k] = *(const PG8_LAS bf16x8*)(lds + PG8_SA(b, h) + aoff + m * 2048 + k * 1024); } while (0)
; #define PG8_LDB(dst, b, h) do { _Pragma("unroll") for (int n = 0; n < 2; ++n) _Pragma("unroll") for (int k = 0; k < 2; ++k) dst[n][k] = *(const PG8_LAS bf16x8*)(lds + PG8_SB(b, h) + boff + n * 2048 + k * 1024); } while (0)
; #define PG8_MMA(ai, bj, At, Bt) do { __builtin_amdgcn_s_setprio(1); _Pragma("unroll") for (int m = 0; m < 4; ++m) _Pragma("unroll") for (int n = 0; n < 2; ++n) _Pragma("unroll") for (int k = 0; k < 2; ++k) \
;         acc[ai][bj][m][n] = __builtin_amdgcn_mfma_f32_16x16x32_bf16(Bt[n][k], At[m][k], acc[ai][bj][m][n], 0, 0, 0); __builtin_amdgcn_s_setprio(0); } while (0)
; #define PG8_WAIT_V(n) asm volatile("s_waitcnt vmcnt(" #n ")" ::: "memory")
; #define PG8_WAIT_L(n) asm volatile("s_waitcnt lgkmcnt(" #n ")" ::: "memory")
; #define PG8_BAR __builtin_amdgcn_s_barrier()
; #define PG8_SCHED __builtin_amdgcn_sched_barrier(0)
; template <class Epi, class Sched, bool ALIGN_EPI = false, bool SP2 = false>
; __device__ __forceinline__ void gemm_phase(PG8_LAS unsigned char* lds, const Gemm g, const Sched S, const Epi E) {
;     ...
;             if constexpr (SP2) {
;             PG8_LDB(B0, 0, 0); PG8_LDB(B1, 0, 1); PG8_SCHED; PG8_LDA(At, 0, 0); PG8_STAGE(PG8_SA(1, 1), a1 + hstep, voffA);
;             PG8_WAIT_V(8); PG8_WAIT_L(0); PG8_BAR; PG8_MMA(0, 0, At, B0); PG8_MMA(0, 1, At, B1); PG8_BAR; PG8_SCHED;
;             PG8_LDA(At, 0, 1); PG8_STAGE(PG8_SB(0, 0), b2, voffB); PG8_STAGE(PG8_SB(0, 1), b2 + hstep, voffB); PG8_STAGE(PG8_SA(0, 0), a2, voffA);
;             PG8_WAIT_V(8); PG8_WAIT_L(0); PG8_BAR; PG8_MMA(1, 0, At, B0); PG8_MMA(1, 1, At, B1); PG8_BAR; PG8_SCHED;
.Lpagefit_6:
.LBB0_1025:
	ds_read_b128 v[152:155], v149
	ds_read_b128 v[156:159], v149 offset:1024
	ds_read_b128 v[160:163], v149 offset:2048
	ds_read_b128 v[164:167], v149 offset:3072
	ds_read_b128 v[168:171], v150
	ds_read_b128 v[172:175], v150 offset:1024
	ds_read_b128 v[176:179], v150 offset:2048
	ds_read_b128 v[180:183], v150 offset:3072
	s_add_u32 s42, s40, 0xfffc0080
	s_addc_u32 s43, s41, -1
	s_cmp_eq_u32 s63, 12
	s_cselect_b32 s45, s19, s43
	s_cselect_b32 s44, s59, s42
	s_cselect_b32 s43, s17, s62
	s_cselect_b32 s42, s60, s61
	v_lshl_add_u64 v[144:145], s[40:41], 0, v[136:137]
	s_add_i32 m0, s12, 0xc000
	ds_read_b128 v[190:193], v151
	ds_read_b128 v[194:197], v151 offset:1024
	ds_read_b128 v[198:201], v151 offset:2048
	ds_read_b128 v[202:205], v151 offset:3072
	ds_read_b128 v[206:209], v151 offset:4096
	ds_read_b128 v[210:213], v151 offset:5120
	ds_read_b128 v[214:217], v151 offset:6144
	ds_read_b128 v[218:221], v151 offset:7168
	global_load_lds_dwordx4 v[144:145], off
	v_lshl_add_u64 v[144:145], s[40:41], 0, v[138:139]
	s_add_i32 m0, s12, 0xe000
	s_nop 0
	global_load_lds_dwordx4 v[144:145], off
	s_waitcnt vmcnt(8)
	s_waitcnt lgkmcnt(0)
	s_barrier
	s_setprio 1
	s_waitcnt lgkmcnt(0)
	v_mfma_f32_16x16x32_bf16 v[124:127], v[152:155], v[190:193], v[124:127]
	v_mfma_f32_16x16x32_bf16 v[116:119], v[160:163], v[190:193], v[116:119]
	v_mfma_f32_16x16x32_bf16 v[108:111], v[152:155], v[198:201], v[108:111]
	v_mfma_f32_16x16x32_bf16 v[100:103], v[160:163], v[198:201], v[100:103]
	v_mfma_f32_16x16x32_bf16 v[92:95], v[152:155], v[206:209], v[92:95]
	v_mfma_f32_16x16x32_bf16 v[84:87], v[160:163], v[206:209], v[84:87]
	v_mfma_f32_16x16x32_bf16 v[76:79], v[152:155], v[214:217], v[76:79]
	v_mfma_f32_16x16x32_bf16 v[68:71], v[160:163], v[214:217], v[68:71]
	v_mfma_f32_16x16x32_bf16 v[124:127], v[156:159], v[194:197], v[124:127]
	v_mfma_f32_16x16x32_bf16 v[116:119], v[164:167], v[194:197], v[116:119]
	v_mfma_f32_16x16x32_bf16 v[108:111], v[156:159], v[202:205], v[108:111]
	v_mfma_f32_16x16x32_bf16 v[100:103], v[164:167], v[202:205], v[100:103]
	v_mfma_f32_16x16x32_bf16 v[92:95], v[156:159], v[210:213], v[92:95]
	v_mfma_f32_16x16x32_bf16 v[84:87], v[164:167], v[210:213], v[84:87]
	v_mfma_f32_16x16x32_bf16 v[76:79], v[156:159], v[218:221], v[76:79]
	v_mfma_f32_16x16x32_bf16 v[68:71], v[164:167], v[218:221], v[68:71]
	s_setprio 0
	s_setprio 1
	v_mfma_f32_16x16x32_bf16 v[120:123], v[168:171], v[190:193], v[120:123]
	v_mfma_f32_16x16x32_bf16 v[112:115], v[176:179], v[190:193], v[112:115]
	v_mfma_f32_16x16x32_bf16 v[104:107], v[168:171], v[198:201], v[104:107]
	v_mfma_f32_16x16x32_bf16 v[96:99], v[176:179], v[198:201], v[96:99]
	v_mfma_f32_16x16x32_bf16 v[88:91], v[168:171], v[206:209], v[88:91]
	v_mfma_f32_16x16x32_bf16 v[80:83], v[176:179], v[206:209], v[80:83]
	v_mfma_f32_16x16x32_bf16 v[72:75], v[168:171], v[214:217], v[72:75]
	v_mfma_f32_16x16x32_bf16 v[64:67], v[176:179], v[214:217], v[64:67]
	v_mfma_f32_16x16x32_bf16 v[120:123], v[172:175], v[194:197], v[120:123]
	v_mfma_f32_16x16x32_bf16 v[112:115], v[180:183], v[194:197], v[112:115]
	v_mfma_f32_16x16x32_bf16 v[104:107], v[172:175], v[202:205], v[104:107]
	v_mfma_f32_16x16x32_bf16 v[96:99], v[180:183], v[202:205], v[96:99]
	v_mfma_f32_16x16x32_bf16 v[88:91], v[172:175], v[210:213], v[88:91]
	v_mfma_f32_16x16x32_bf16 v[80:83], v[180:183], v[210:213], v[80:83]
	v_mfma_f32_16x16x32_bf16 v[72:75], v[172:175], v[218:221], v[72:75]
	v_mfma_f32_16x16x32_bf16 v[64:67], v[180:183], v[218:221], v[64:67]
	s_setprio 0
	s_barrier
	s_add_i32 s64, s53, s8
	v_lshl_add_u64 v[144:145], s[42:43], 0, v[132:133]
	s_mov_b32 m0, s64
	ds_read_b128 v[190:193], v151 offset:16384
	ds_read_b128 v[194:197], v151 offset:17408
	ds_read_b128 v[198:201], v151 offset:18432
	ds_read_b128 v[202:205], v151 offset:19456
	ds_read_b128 v[206:209], v151 offset:20480
	ds_read_b128 v[210:213], v151 offset:21504
	ds_read_b128 v[214:217], v151 offset:22528
	ds_read_b128 v[218:221], v151 offset:23552
	global_load_lds_dwordx4 v[144:145], off
	s_add_i32 m0, s64, 0x2000
	s_add_u32 s64, s42, 0x40000
	v_lshl_add_u64 v[184:185], s[42:43], 0, v[128:129]
	s_addc_u32 s65, s43, 0
	s_add_i32 s66, s54, s8
	global_load_lds_dwordx4 v[184:185], off
	v_lshl_add_u64 v[186:187], s[64:65], 0, v[132:133]
	s_mov_b32 m0, s66
	v_lshl_add_u64 v[222:223], s[44:45], 0, v[130:131]
	global_load_lds_dwordx4 v[186:187], off
	v_lshl_add_u64 v[186:187], s[64:65], 0, v[128:129]
	s_add_i32 m0, s66, 0x2000
	s_nop 0
	global_load_lds_dwordx4 v[186:187], off
	v_lshl_add_u64 v[186:187], s[44:45], 0, v[134:135]
	s_mov_b32 m0, s12
	s_nop 0
	global_load_lds_dwordx4 v[186:187], off
	s_mov_b32 m0, s13
	s_nop 0
	global_load_lds_dwordx4 v[222:223], off
	s_waitcnt vmcnt(8)
	s_waitcnt lgkmcnt(0)
	s_barrier
; #define PG8_STAGE(bufoff, gbase, voff) do { _Pragma("unroll") for (int _i = 0; _i < 2; ++_i) \
;         __builtin_amdgcn_global_load_lds((const unsigned*)((const char*)(gbase) + (voff)[_i]), (PG8_LAS unsigned*)(lds + (bufoff) + ldsw + _i * 8192), 16, 0, 0); } while (0)
; #define PG8_LDA(dst, b, h) do { _Pragma("unroll") for (int m = 0; m < 4; ++m) _Pragma("unroll") for (int k = 0; k < 2; ++k) dst[m][k] = *(const PG8_LAS bf16x8*)(lds + PG8_SA(b, h) + aoff + m * 2048 + k * 1024); } while (0)
; #define PG8_LDB(dst, b, h) do { _Pragma("unroll") for (int n = 0; n < 2; ++n) _Pragma("unroll") for (int k = 0; k < 2; ++k) dst[n][k] = *(const PG8_LAS bf16x8*)(lds + PG8_SB(b, h) + boff + n * 2048 + k * 1024); } while (0)
; #define PG8_MMA(ai, bj, At, Bt) do { __builtin_amdgcn_s_setprio(1); _Pragma("unroll") for (int m = 0; m < 4; ++m) _Pragma("unroll") for (int n = 0; n < 2; ++n) _Pragma("unroll") for (int k = 0; k < 2; ++k) \
;         acc[ai][bj][m][n] = __builtin_amdgcn_mfma_f32_16x16x32_bf16(Bt[n][k], At[m][k], acc[ai][bj][m][n], 0, 0, 0); __builtin_amdgcn_s_setprio(0); } while (0)
; #define PG8_WAIT_V(n) asm volatile("s_waitcnt vmcnt(" #n ")" ::: "memory")
; #define PG8_WAIT_L(n) asm volatile("s_waitcnt lgkmcnt(" #n ")" ::: "memory")
; #define PG8_BAR __builtin_amdgcn_s_barrier()
; #define PG8_SCHED __builtin_amdgcn_sched_barrier(0)
; template <class Epi, class Sched, bool ALIGN_EPI = false, bool SP2 = false>
; __device__ __forceinline__ void gemm_phase(PG8_LAS unsigned char* lds, const Gemm g, const Sched S, const Epi E) {
;     ...
;             PG8_WAIT_V(8); PG8_WAIT_L(0); PG8_BAR; PG8_MMA(1, 0, At, B0); PG8_MMA(1, 1, At, B1); PG8_BAR; PG8_SCHED;
;             PG8_LDB(B0, 1, 0); PG8_LDB(B1, 1, 1); PG8_SCHED; PG8_LDA(At, 1, 0); PG8_STAGE(PG8_SA(0, 1), a2 + hstep, voffA);
;             PG8_WAIT_V(8); PG8_WAIT_L(0); PG8_BAR; PG8_MMA(0, 0, At, B0); PG8_MMA(0, 1, At, B1); PG8_BAR; PG8_SCHED;
	s_setprio 1
	s_waitcnt lgkmcnt(0)
	v_mfma_f32_16x16x32_bf16 v[60:63], v[152:155], v[190:193], v[60:63]
	v_mfma_f32_16x16x32_bf16 v[52:55], v[160:163], v[190:193], v[52:55]
	v_mfma_f32_16x16x32_bf16 v[44:47], v[152:155], v[198:201], v[44:47]
	v_mfma_f32_16x16x32_bf16 v[36:39], v[160:163], v[198:201], v[36:39]
	v_mfma_f32_16x16x32_bf16 v[28:31], v[152:155], v[206:209], v[28:31]
	v_mfma_f32_16x16x32_bf16 v[20:23], v[160:163], v[206:209], v[20:23]
	v_mfma_f32_16x16x32_bf16 v[12:15], v[152:155], v[214:217], v[12:15]
	v_mfma_f32_16x16x32_bf16 v[4:7], v[160:163], v[214:217], v[4:7]
	v_mfma_f32_16x16x32_bf16 v[60:63], v[156:159], v[194:197], v[60:63]
	v_mfma_f32_16x16x32_bf16 v[52:55], v[164:167], v[194:197], v[52:55]
	v_mfma_f32_16x16x32_bf16 v[44:47], v[156:159], v[202:205], v[44:47]
	v_mfma_f32_16x16x32_bf16 v[36:39], v[164:167], v[202:205], v[36:39]
	v_mfma_f32_16x16x32_bf16 v[28:31], v[156:159], v[210:213], v[28:31]
	v_mfma_f32_16x16x32_bf16 v[20:23], v[164:167], v[210:213], v[20:23]
	v_mfma_f32_16x16x32_bf16 v[12:15], v[156:159], v[218:221], v[12:15]
	v_mfma_f32_16x16x32_bf16 v[4:7], v[164:167], v[218:221], v[4:7]
	s_setprio 0
	s_setprio 1
	v_mfma_f32_16x16x32_bf16 v[56:59], v[168:171], v[190:193], v[56:59]
	v_mfma_f32_16x16x32_bf16 v[48:51], v[176:179], v[190:193], v[48:51]
	v_mfma_f32_16x16x32_bf16 v[40:43], v[168:171], v[198:201], v[40:43]
	v_mfma_f32_16x16x32_bf16 v[32:35], v[176:179], v[198:201], v[32:35]
	v_mfma_f32_16x16x32_bf16 v[24:27], v[168:171], v[206:209], v[24:27]
	v_mfma_f32_16x16x32_bf16 v[16:19], v[176:179], v[206:209], v[16:19]
	v_mfma_f32_16x16x32_bf16 v[8:11], v[168:171], v[214:217], v[8:11]
	v_mfma_f32_16x16x32_bf16 v[0:3], v[176:179], v[214:217], v[0:3]
	v_mfma_f32_16x16x32_bf16 v[56:59], v[172:175], v[194:197], v[56:59]
	v_mfma_f32_16x16x32_bf16 v[48:51], v[180:183], v[194:197], v[48:51]
	v_mfma_f32_16x16x32_bf16 v[40:43], v[172:175], v[202:205], v[40:43]
	v_mfma_f32_16x16x32_bf16 v[32:35], v[180:183], v[202:205], v[32:35]
	v_mfma_f32_16x16x32_bf16 v[24:27], v[172:175], v[210:213], v[24:27]
	v_mfma_f32_16x16x32_bf16 v[16:19], v[180:183], v[210:213], v[16:19]
	v_mfma_f32_16x16x32_bf16 v[8:11], v[172:175], v[218:221], v[8:11]
	v_mfma_f32_16x16x32_bf16 v[0:3], v[180:183], v[218:221], v[0:3]
	s_setprio 0
	s_barrier
	s_add_i32 s64, 0, 0x18000
	s_add_i32 s65, 0, 0x1c000
	v_add_u32_e32 v164, s64, v148
	v_add_u32_e32 v180, s65, v148
	ds_read_b128 v[152:155], v164
	ds_read_b128 v[156:159], v164 offset:1024
	ds_read_b128 v[160:163], v164 offset:2048
	ds_read_b128 v[164:167], v164 offset:3072
	ds_read_b128 v[168:171], v180
	ds_read_b128 v[172:175], v180 offset:1024
	ds_read_b128 v[176:179], v180 offset:2048
	ds_read_b128 v[180:183], v180 offset:3072
	s_add_u32 s44, s44, 0x40000
	s_addc_u32 s45, s45, 0
	s_mov_b32 m0, s33
	v_lshl_add_u64 v[224:225], s[44:45], 0, v[134:135]
	ds_read_b128 v[190:193], v151 offset:32768
	ds_read_b128 v[194:197], v151 offset:33792
	ds_read_b128 v[198:201], v151 offset:34816
	ds_read_b128 v[202:205], v151 offset:35840
	ds_read_b128 v[206:209], v151 offset:36864
	ds_read_b128 v[210:213], v151 offset:37888
	ds_read_b128 v[214:217], v151 offset:38912
	ds_read_b128 v[218:221], v151 offset:39936
	global_load_lds_dwordx4 v[224:225], off
	v_lshl_add_u64 v[224:225], s[44:45], 0, v[130:131]
	s_mov_b32 m0, s39
	s_nop 0
	global_load_lds_dwordx4 v[224:225], off
	s_waitcnt vmcnt(8)
	s_waitcnt lgkmcnt(0)
	s_barrier
	s_setprio 1
	s_waitcnt lgkmcnt(0)
	v_mfma_f32_16x16x32_bf16 v[124:127], v[152:155], v[190:193], v[124:127]
	v_mfma_f32_16x16x32_bf16 v[116:119], v[160:163], v[190:193], v[116:119]
	v_mfma_f32_16x16x32_bf16 v[108:111], v[152:155], v[198:201], v[108:111]
	v_mfma_f32_16x16x32_bf16 v[100:103], v[160:163], v[198:201], v[100:103]
	v_mfma_f32_16x16x32_bf16 v[92:95], v[152:155], v[206:209], v[92:95]
	v_mfma_f32_16x16x32_bf16 v[84:87], v[160:163], v[206:209], v[84:87]
	v_mfma_f32_16x16x32_bf16 v[76:79], v[152:155], v[214:217], v[76:79]
	v_mfma_f32_16x16x32_bf16 v[68:71], v[160:163], v[214:217], v[68:71]
	v_mfma_f32_16x16x32_bf16 v[124:127], v[156:159], v[194:197], v[124:127]
	v_mfma_f32_16x16x32_bf16 v[116:119], v[164:167], v[194:197], v[116:119]
	v_mfma_f32_16x16x32_bf16 v[108:111], v[156:159], v[202:205], v[108:111]
	v_mfma_f32_16x16x32_bf16 v[100:103], v[164:167], v[202:205], v[100:103]
	v_mfma_f32_16x16x32_bf16 v[92:95], v[156:159], v[210:213], v[92:95]
	v_mfma_f32_16x16x32_bf16 v[84:87], v[164:167], v[210:213], v[84:87]
	v_mfma_f32_16x16x32_bf16 v[76:79], v[156:159], v[218:221], v[76:79]
	v_mfma_f32_16x16x32_bf16 v[68:71], v[164:167], v[218:221], v[68:71]
	s_setprio 0
	s_setprio 1
	v_mfma_f32_16x16x32_bf16 v[120:123], v[168:171], v[190:193], v[120:123]
	v_mfma_f32_16x16x32_bf16 v[112:115], v[176:179], v[190:193], v[112:115]
	v_mfma_f32_16x16x32_bf16 v[104:107], v[168:171], v[198:201], v[104:107]
	v_mfma_f32_16x16x32_bf16 v[96:99], v[176:179], v[198:201], v[96:99]
	v_mfma_f32_16x16x32_bf16 v[88:91], v[168:171], v[206:209], v[88:91]
	v_mfma_f32_16x16x32_bf16 v[80:83], v[176:179], v[206:209], v[80:83]
	v_mfma_f32_16x16x32_bf16 v[72:75], v[168:171], v[214:217], v[72:75]
	v_mfma_f32_16x16x32_bf16 v[64:67], v[176:179], v[214:217], v[64:67]
	v_mfma_f32_16x16x32_bf16 v[120:123], v[172:175], v[194:197], v[120:123]
	v_mfma_f32_16x16x32_bf16 v[112:115], v[180:183], v[194:197], v[112:115]
	v_mfma_f32_16x16x32_bf16 v[104:107], v[172:175], v[202:205], v[104:107]
	v_mfma_f32_16x16x32_bf16 v[96:99], v[180:183], v[202:205], v[96:99]
	v_mfma_f32_16x16x32_bf16 v[88:91], v[172:175], v[210:213], v[88:91]
	v_mfma_f32_16x16x32_bf16 v[80:83], v[180:183], v[210:213], v[80:83]
	v_mfma_f32_16x16x32_bf16 v[72:75], v[172:175], v[218:221], v[72:75]
	v_mfma_f32_16x16x32_bf16 v[64:67], v[180:183], v[218:221], v[64:67]
	s_setprio 0
	s_barrier
; #define PG8_STAGE(bufoff, gbase, voff) do { _Pragma("unroll") for (int _i = 0; _i < 2; ++_i) \
;         __builtin_amdgcn_global_load_lds((const unsigned*)((const char*)(gbase) + (voff)[_i]), (PG8_LAS unsigned*)(lds + (bufoff) + ldsw + _i * 8192), 16, 0, 0); } while (0)
; #define PG8_LDA(dst, b, h) do { _Pragma("unroll") for (int m = 0; m < 4; ++m) _Pragma("unroll") for (int k = 0; k < 2; ++k) dst[m][k] = *(const PG8_LAS bf16x8*)(lds + PG8_SA(b, h) + aoff + m * 2048 + k * 1024); } while (0)
; #define PG8_MMA(ai, bj, At, Bt) do { __builtin_amdgcn_s_setprio(1); _Pragma("unroll") for (int m = 0; m < 4; ++m) _Pragma("unroll") for (int n = 0; n < 2; ++n) _Pragma("unroll") for (int k = 0; k < 2; ++k) \
;         acc[ai][bj][m][n] = __builtin_amdgcn_mfma_f32_16x16x32_bf16(Bt[n][k], At[m][k], acc[ai][bj][m][n], 0, 0, 0); __builtin_amdgcn_s_setprio(0); } while (0)
; #define PG8_WAIT_V(n) asm volatile("s_waitcnt vmcnt(" #n ")" ::: "memory")
; #define PG8_WAIT_L(n) asm volatile("s_waitcnt lgkmcnt(" #n ")" ::: "memory")
; #define PG8_BAR __builtin_amdgcn_s_barrier()
; #define PG8_SCHED __builtin_amdgcn_sched_barrier(0)
; template <class Epi, class Sched, bool ALIGN_EPI = false, bool SP2 = false>
; __device__ __forceinline__ void gemm_phase(PG8_LAS unsigned char* lds, const Gemm g, const Sched S, const Epi E) {
;     ...
;         for (int t = 0; t < nt; t += 2) {
;     ...
;             PG8_WAIT_V(8); PG8_WAIT_L(0); PG8_BAR; PG8_MMA(0, 0, At, B0); PG8_MMA(0, 1, At, B1); PG8_BAR; PG8_SCHED;
;             PG8_LDA(At, 1, 1); PG8_STAGE(PG8_SB(1, 0), b3, voffB); PG8_STAGE(PG8_SB(1, 1), b3 + hstep, voffB); PG8_STAGE(PG8_SA(1, 0), a3, voffA);
;             PG8_WAIT_V(8); PG8_WAIT_L(0); PG8_BAR; PG8_MMA(1, 0, At, B0); PG8_MMA(1, 1, At, B1); PG8_BAR; PG8_SCHED;
;     ...
;         if constexpr (ALIGN_EPI) { if (wr == 0) PG8_BAR; }
	s_add_i32 s44, s64, s8
	v_lshl_add_u64 v[144:145], v[144:145], 0, s[10:11]
	s_mov_b32 m0, s44
	ds_read_b128 v[190:193], v151 offset:49152
	ds_read_b128 v[194:197], v151 offset:50176
	ds_read_b128 v[198:201], v151 offset:51200
	ds_read_b128 v[202:205], v151 offset:52224
	ds_read_b128 v[206:209], v151 offset:53248
	ds_read_b128 v[210:213], v151 offset:54272
	ds_read_b128 v[214:217], v151 offset:55296
	ds_read_b128 v[218:221], v151 offset:56320
	global_load_lds_dwordx4 v[144:145], off
	s_add_i32 m0, s44, 0x2000
	s_add_u32 s42, s42, 0x40080
	v_lshl_add_u64 v[144:145], v[184:185], 0, s[10:11]
	s_addc_u32 s43, s43, 0
	s_add_i32 s44, s65, s8
	global_load_lds_dwordx4 v[144:145], off
	v_lshl_add_u64 v[144:145], s[42:43], 0, v[132:133]
	s_mov_b32 m0, s44
	s_nop 0
	global_load_lds_dwordx4 v[144:145], off
	v_lshl_add_u64 v[144:145], s[42:43], 0, v[128:129]
	s_add_i32 m0, s44, 0x2000
	s_nop 0
	global_load_lds_dwordx4 v[144:145], off
	v_lshl_add_u64 v[144:145], v[186:187], 0, s[10:11]
	s_mov_b32 m0, s49
	s_nop 0
	global_load_lds_dwordx4 v[144:145], off
	v_lshl_add_u64 v[144:145], v[222:223], 0, s[10:11]
	s_mov_b32 m0, s50
	s_nop 0
	global_load_lds_dwordx4 v[144:145], off
	s_waitcnt vmcnt(8)
	s_waitcnt lgkmcnt(0)
	s_barrier
	s_setprio 1
	s_waitcnt lgkmcnt(0)
	v_mfma_f32_16x16x32_bf16 v[60:63], v[152:155], v[190:193], v[60:63]
	v_mfma_f32_16x16x32_bf16 v[52:55], v[160:163], v[190:193], v[52:55]
	v_mfma_f32_16x16x32_bf16 v[44:47], v[152:155], v[198:201], v[44:47]
	v_mfma_f32_16x16x32_bf16 v[36:39], v[160:163], v[198:201], v[36:39]
	v_mfma_f32_16x16x32_bf16 v[28:31], v[152:155], v[206:209], v[28:31]
	v_mfma_f32_16x16x32_bf16 v[20:23], v[160:163], v[206:209], v[20:23]
	v_mfma_f32_16x16x32_bf16 v[12:15], v[152:155], v[214:217], v[12:15]
	v_mfma_f32_16x16x32_bf16 v[4:7], v[160:163], v[214:217], v[4:7]
	v_mfma_f32_16x16x32_bf16 v[60:63], v[156:159], v[194:197], v[60:63]
	v_mfma_f32_16x16x32_bf16 v[52:55], v[164:167], v[194:197], v[52:55]
	v_mfma_f32_16x16x32_bf16 v[44:47], v[156:159], v[202:205], v[44:47]
	v_mfma_f32_16x16x32_bf16 v[36:39], v[164:167], v[202:205], v[36:39]
	v_mfma_f32_16x16x32_bf16 v[28:31], v[156:159], v[210:213], v[28:31]
	v_mfma_f32_16x16x32_bf16 v[20:23], v[164:167], v[210:213], v[20:23]
	v_mfma_f32_16x16x32_bf16 v[12:15], v[156:159], v[218:221], v[12:15]
	v_mfma_f32_16x16x32_bf16 v[4:7], v[164:167], v[218:221], v[4:7]
	s_setprio 0
	s_setprio 1
	v_mfma_f32_16x16x32_bf16 v[56:59], v[168:171], v[190:193], v[56:59]
	v_mfma_f32_16x16x32_bf16 v[48:51], v[176:179], v[190:193], v[48:51]
	v_mfma_f32_16x16x32_bf16 v[40:43], v[168:171], v[198:201], v[40:43]
	v_mfma_f32_16x16x32_bf16 v[32:35], v[176:179], v[198:201], v[32:35]
	v_mfma_f32_16x16x32_bf16 v[24:27], v[168:171], v[206:209], v[24:27]
	v_mfma_f32_16x16x32_bf16 v[16:19], v[176:179], v[206:209], v[16:19]
	v_mfma_f32_16x16x32_bf16 v[8:11], v[168:171], v[214:217], v[8:11]
	v_mfma_f32_16x16x32_bf16 v[0:3], v[176:179], v[214:217], v[0:3]
	v_mfma_f32_16x16x32_bf16 v[56:59], v[172:175], v[194:197], v[56:59]
	v_mfma_f32_16x16x32_bf16 v[48:51], v[180:183], v[194:197], v[48:51]
	v_mfma_f32_16x16x32_bf16 v[40:43], v[172:175], v[202:205], v[40:43]
	v_mfma_f32_16x16x32_bf16 v[32:35], v[180:183], v[202:205], v[32:35]
	v_mfma_f32_16x16x32_bf16 v[24:27], v[172:175], v[210:213], v[24:27]
	v_mfma_f32_16x16x32_bf16 v[16:19], v[180:183], v[210:213], v[16:19]
	v_mfma_f32_16x16x32_bf16 v[8:11], v[172:175], v[218:221], v[8:11]
	v_mfma_f32_16x16x32_bf16 v[0:3], v[180:183], v[218:221], v[0:3]
	s_setprio 0
	s_barrier
	s_add_i32 s63, s63, 2
	s_add_u32 s40, s40, 0x100
	s_addc_u32 s41, s41, 0
	s_add_u32 s61, s61, 0x100
	s_addc_u32 s62, s62, 0
	s_cmp_gt_u32 s63, 13
	s_cbranch_scc0 .LBB0_1025
	s_and_b64 vcc, exec, s[14:15]
	s_cbranch_vccz .LBB0_1028
	s_barrier
